# RG-LRU unit prologue: gate-weight staging loop (pointer load, wait, 4 weight loads, wait per iteration) replaced by straight-line code with both pointers loaded once and all 32 weight loads in flight
# speedup vs baseline: 1.0102x; 1.0016x over previous
; __device__ __forceinline__ bf16_t f2bf(float f) { return (bf16_t)(cvt_pk_bf16(f, 0.f) & 0xffffu); }
; __device__ __forceinline__ void rglru_unit(const Params& p, const WS& ws, int j, int u, bool dry = false) {
;     ...
; #pragma unroll 4
;   for (int i = 0; i < 32; ++i) {
;     const int e = tid + 256 * i;
;     const int gate = e >> 12, k = (e >> 5) & 127, n = e & 31;
;     const float* gw = gate ? p.ab_gate_x_w : p.ab_gate_a_w;
;     WG[(gate * 32 + n) * 136 + k] = f2bf(gw[((size_t)(j * 8 + g) * 128 + k) * 128 + 32 * jq + n]);
;   }
.LBB0_1320:
	s_waitcnt vmcnt(0)
	global_load_dwordx2 v[0:1], v12, s[0:1] offset:56
	global_load_dwordx2 v[2:3], v12, s[0:1] offset:72
	s_lshl_b32 s92, s9, 2
	v_lshrrev_b32_e32 v13, 5, v61
	v_lshlrev_b32_e32 v10, 2, v60
	v_mov_b32_e32 v11, v12
	v_lshlrev_b32_e32 v14, 9, v13
	v_mov_b32_e32 v15, v12
	v_mul_u32_u24_e32 v16, 0x110, v60
	v_lshl_add_u32 v16, v13, 1, v16
	v_add_u32_e32 v16, s8, v16
	v_add_u32_e32 v17, 0x2200, v16
	s_mov_b32 s100, 0x1000
	s_mov_b32 s101, 0
	s_waitcnt vmcnt(0)
	v_lshl_add_u64 v[4:5], v[0:1], 0, s[4:5]
	v_lshl_add_u64 v[6:7], v[2:3], 0, s[4:5]
	v_lshl_add_u64 v[4:5], v[4:5], 0, s[92:93]
	v_lshl_add_u64 v[6:7], v[6:7], 0, s[92:93]
	v_lshl_add_u64 v[4:5], v[4:5], 0, v[10:11]
	v_lshl_add_u64 v[6:7], v[6:7], 0, v[10:11]
	v_lshl_add_u64 v[4:5], v[4:5], 0, v[14:15]
	v_lshl_add_u64 v[6:7], v[6:7], 0, v[14:15]
	global_load_dword v210, v[4:5], off
	global_load_dword v226, v[6:7], off
	v_lshl_add_u64 v[4:5], v[4:5], 0, s[100:101]
	v_lshl_add_u64 v[6:7], v[6:7], 0, s[100:101]
	global_load_dword v211, v[4:5], off
	global_load_dword v227, v[6:7], off
	v_lshl_add_u64 v[4:5], v[4:5], 0, s[100:101]
	v_lshl_add_u64 v[6:7], v[6:7], 0, s[100:101]
	global_load_dword v212, v[4:5], off
	global_load_dword v228, v[6:7], off
	v_lshl_add_u64 v[4:5], v[4:5], 0, s[100:101]
	v_lshl_add_u64 v[6:7], v[6:7], 0, s[100:101]
	global_load_dword v213, v[4:5], off
	global_load_dword v229, v[6:7], off
	v_lshl_add_u64 v[4:5], v[4:5], 0, s[100:101]
	v_lshl_add_u64 v[6:7], v[6:7], 0, s[100:101]
	global_load_dword v214, v[4:5], off
	global_load_dword v230, v[6:7], off
	v_lshl_add_u64 v[4:5], v[4:5], 0, s[100:101]
	v_lshl_add_u64 v[6:7], v[6:7], 0, s[100:101]
	global_load_dword v215, v[4:5], off
	global_load_dword v231, v[6:7], off
	v_lshl_add_u64 v[4:5], v[4:5], 0, s[100:101]
	v_lshl_add_u64 v[6:7], v[6:7], 0, s[100:101]
	global_load_dword v216, v[4:5], off
	global_load_dword v232, v[6:7], off
	v_lshl_add_u64 v[4:5], v[4:5], 0, s[100:101]
	v_lshl_add_u64 v[6:7], v[6:7], 0, s[100:101]
	global_load_dword v217, v[4:5], off
	global_load_dword v233, v[6:7], off
	v_lshl_add_u64 v[4:5], v[4:5], 0, s[100:101]
	v_lshl_add_u64 v[6:7], v[6:7], 0, s[100:101]
	global_load_dword v218, v[4:5], off
	global_load_dword v234, v[6:7], off
	v_lshl_add_u64 v[4:5], v[4:5], 0, s[100:101]
	v_lshl_add_u64 v[6:7], v[6:7], 0, s[100:101]
	global_load_dword v219, v[4:5], off
	global_load_dword v235, v[6:7], off
	v_lshl_add_u64 v[4:5], v[4:5], 0, s[100:101]
	v_lshl_add_u64 v[6:7], v[6:7], 0, s[100:101]
	global_load_dword v220, v[4:5], off
	global_load_dword v242, v[6:7], off
	v_lshl_add_u64 v[4:5], v[4:5], 0, s[100:101]
	v_lshl_add_u64 v[6:7], v[6:7], 0, s[100:101]
	global_load_dword v221, v[4:5], off
	global_load_dword v243, v[6:7], off
	v_lshl_add_u64 v[4:5], v[4:5], 0, s[100:101]
	v_lshl_add_u64 v[6:7], v[6:7], 0, s[100:101]
	global_load_dword v222, v[4:5], off
	global_load_dword v244, v[6:7], off
	v_lshl_add_u64 v[4:5], v[4:5], 0, s[100:101]
	v_lshl_add_u64 v[6:7], v[6:7], 0, s[100:101]
	global_load_dword v223, v[4:5], off
	global_load_dword v245, v[6:7], off
	v_lshl_add_u64 v[4:5], v[4:5], 0, s[100:101]
	v_lshl_add_u64 v[6:7], v[6:7], 0, s[100:101]
	global_load_dword v224, v[4:5], off
	global_load_dword v246, v[6:7], off
	v_lshl_add_u64 v[4:5], v[4:5], 0, s[100:101]
	v_lshl_add_u64 v[6:7], v[6:7], 0, s[100:101]
	global_load_dword v225, v[4:5], off
	global_load_dword v247, v[6:7], off
	s_waitcnt vmcnt(31)
	v_cvt_pk_bf16_f32 v0, v210, s0
	ds_write_b16 v16, v0 offset:17408
	s_waitcnt vmcnt(30)
	v_cvt_pk_bf16_f32 v1, v226, s0
	ds_write_b16 v17, v1 offset:17408
	s_waitcnt vmcnt(29)
	v_cvt_pk_bf16_f32 v2, v211, s0
	ds_write_b16 v16, v2 offset:17424
	s_waitcnt vmcnt(28)
	v_cvt_pk_bf16_f32 v3, v227, s0
	ds_write_b16 v17, v3 offset:17424
	s_waitcnt vmcnt(27)
	v_cvt_pk_bf16_f32 v0, v212, s0
	ds_write_b16 v16, v0 offset:17440
	s_waitcnt vmcnt(26)
	v_cvt_pk_bf16_f32 v1, v228, s0
	ds_write_b16 v17, v1 offset:17440
	s_waitcnt vmcnt(25)
; __device__ __forceinline__ bf16_t f2bf(float f) { return (bf16_t)(cvt_pk_bf16(f, 0.f) & 0xffffu); }
; __device__ __forceinline__ void rglru_unit(const Params& p, const WS& ws, int j, int u, bool dry = false) {
;     ...
; #pragma unroll 4
;   for (int i = 0; i < 32; ++i) {
;     const int e = tid + 256 * i;
;     const int gate = e >> 12, k = (e >> 5) & 127, n = e & 31;
;     const float* gw = gate ? p.ab_gate_x_w : p.ab_gate_a_w;
;     WG[(gate * 32 + n) * 136 + k] = f2bf(gw[((size_t)(j * 8 + g) * 128 + k) * 128 + 32 * jq + n]);
;   }
;   if (tid < 32) CARRY[tid] = 0.f;
;   float ba[2][4], bx[2][4], sp[2][4];
; #pragma unroll
;   for (int mt = 0; mt < 2; ++mt)
; #pragma unroll
;     for (int jj = 0; jj < 4; ++jj) {
;       const int ch = j * 1024 + 128 * g + 32 * jq + 16 * mt + 4 * lq + jj;
;       ba[mt][jj] = p.ab_gate_a_b[ch]; bx[mt][jj] = p.ab_gate_x_b[ch];
;       sp[mt][jj] = 8.f * log1pf(__expf(-p.ab_lam[ch]));
;     }
;   const int sc = tid & 31, ssg = tid >> 5;
;   u32x4 xinA[4], xinB[4];
;   bf16_t gavA[8], gavB[8];
;   auto prefetch = [&](int tile, u32x4 (&xin)[4], bf16_t (&gav)[8]) {
;     const int t0 = 64 * tile;
; #pragma unroll
;     for (int i = 0; i < 4; ++i) {
;       const int ci = tid + 256 * i; const int row = ci >> 4, ch = ci & 15; const int t = t0 + row;
;       xin[i] = (u32x4){0, 0, 0, 0};
;       if (t < T_) xin[i] = *(const u32x4*)(ws.XA + (size_t)(b * T_ + t) * 1024 + 128 * g + 8 * ch);
	v_cvt_pk_bf16_f32 v2, v213, s0
	ds_write_b16 v16, v2 offset:17456
	s_waitcnt vmcnt(24)
	v_cvt_pk_bf16_f32 v3, v229, s0
	ds_write_b16 v17, v3 offset:17456
	s_waitcnt vmcnt(23)
	v_cvt_pk_bf16_f32 v0, v214, s0
	ds_write_b16 v16, v0 offset:17472
	s_waitcnt vmcnt(22)
	v_cvt_pk_bf16_f32 v1, v230, s0
	ds_write_b16 v17, v1 offset:17472
	s_waitcnt vmcnt(21)
	v_cvt_pk_bf16_f32 v2, v215, s0
	ds_write_b16 v16, v2 offset:17488
	s_waitcnt vmcnt(20)
	v_cvt_pk_bf16_f32 v3, v231, s0
	ds_write_b16 v17, v3 offset:17488
	s_waitcnt vmcnt(19)
	v_cvt_pk_bf16_f32 v0, v216, s0
	ds_write_b16 v16, v0 offset:17504
	s_waitcnt vmcnt(18)
	v_cvt_pk_bf16_f32 v1, v232, s0
	ds_write_b16 v17, v1 offset:17504
	s_waitcnt vmcnt(17)
	v_cvt_pk_bf16_f32 v2, v217, s0
	ds_write_b16 v16, v2 offset:17520
	s_waitcnt vmcnt(16)
	v_cvt_pk_bf16_f32 v3, v233, s0
	ds_write_b16 v17, v3 offset:17520
	s_waitcnt vmcnt(15)
	v_cvt_pk_bf16_f32 v0, v218, s0
	ds_write_b16 v16, v0 offset:17536
	s_waitcnt vmcnt(14)
	v_cvt_pk_bf16_f32 v1, v234, s0
	ds_write_b16 v17, v1 offset:17536
	s_waitcnt vmcnt(13)
	v_cvt_pk_bf16_f32 v2, v219, s0
	ds_write_b16 v16, v2 offset:17552
	s_waitcnt vmcnt(12)
	v_cvt_pk_bf16_f32 v3, v235, s0
	ds_write_b16 v17, v3 offset:17552
	s_waitcnt vmcnt(11)
	v_cvt_pk_bf16_f32 v0, v220, s0
	ds_write_b16 v16, v0 offset:17568
	s_waitcnt vmcnt(10)
	v_cvt_pk_bf16_f32 v1, v242, s0
	ds_write_b16 v17, v1 offset:17568
	s_waitcnt vmcnt(9)
	v_cvt_pk_bf16_f32 v2, v221, s0
	ds_write_b16 v16, v2 offset:17584
	s_waitcnt vmcnt(8)
	v_cvt_pk_bf16_f32 v3, v243, s0
	ds_write_b16 v17, v3 offset:17584
	s_waitcnt vmcnt(7)
	v_cvt_pk_bf16_f32 v0, v222, s0
	ds_write_b16 v16, v0 offset:17600
	s_waitcnt vmcnt(6)
	v_cvt_pk_bf16_f32 v1, v244, s0
	ds_write_b16 v17, v1 offset:17600
	s_waitcnt vmcnt(5)
	v_cvt_pk_bf16_f32 v2, v223, s0
	ds_write_b16 v16, v2 offset:17616
	s_waitcnt vmcnt(4)
	v_cvt_pk_bf16_f32 v3, v245, s0
	ds_write_b16 v17, v3 offset:17616
	s_waitcnt vmcnt(3)
	v_cvt_pk_bf16_f32 v0, v224, s0
	ds_write_b16 v16, v0 offset:17632
	s_waitcnt vmcnt(2)
	v_cvt_pk_bf16_f32 v1, v246, s0
	ds_write_b16 v17, v1 offset:17632
	s_waitcnt vmcnt(1)
	v_cvt_pk_bf16_f32 v2, v225, s0
	ds_write_b16 v16, v2 offset:17648
	s_waitcnt vmcnt(0)
	v_cvt_pk_bf16_f32 v3, v247, s0
	ds_write_b16 v17, v3 offset:17648
	v_cmp_gt_i32_e32 vcc, 32, v61
	v_lshl_add_u32 v78, v61, 2, s8
	s_and_saveexec_b64 s[4:5], vcc
	ds_write_b32 v78, v12 offset:53760
	s_or_b64 exec, exec, s[4:5]
	s_ashr_i32 s11, s85, 6
	s_add_u32 s4, s12, 0x4284000
	s_addc_u32 s5, s13, 0
	s_lshl_b32 s92, s6, 7
	v_bfe_u32 v64, v61, 4, 2
	s_or_b32 s6, s92, s31
	s_or_b32 s6, s6, s9
	v_lshlrev_b32_e32 v65, 2, v64
	v_or_b32_e32 v0, s6, v65
	s_load_dwordx2 s[6:7], s[0:1], 0x40
	s_load_dwordx8 s[36:43], s[0:1], 0x50
	v_mov_b32_e32 v1, v12
	v_lshlrev_b64 v[0:1], 2, v[0:1]
	v_ashrrev_i32_e32 v79, 4, v61
	s_waitcnt lgkmcnt(0)
	v_lshl_add_u64 v[4:5], s[6:7], 0, v[0:1]
	v_lshl_add_u64 v[14:15], s[36:37], 0, v[0:1]
	v_lshl_add_u64 v[20:21], s[38:39], 0, v[0:1]
	global_load_dwordx4 v[0:3], v[4:5], off
	s_nop 0
	global_load_dwordx4 v[4:7], v[4:5], off offset:64
	s_nop 0
	global_load_dwordx4 v[8:11], v[14:15], off
	global_load_dwordx4 v[16:19], v[14:15], off offset:64
	global_load_dwordx4 v[56:59], v[20:21], off
	global_load_dwordx4 v[52:55], v[20:21], off offset:64
	v_mov_b32_e32 v14, v12
	v_mov_b32_e32 v15, v12
	v_lshlrev_b32_e32 v20, 4, v61
	v_mov_b32_e32 v13, v12
	v_and_b32_e32 v62, 0xf0, v20
	v_mov_b64_e32 v[22:23], v[14:15]
	v_cmp_gt_i32_e32 vcc, s15, v79
	s_mul_i32 s10, s11, 0x810
	v_mov_b64_e32 v[20:21], v[12:13]
	s_and_saveexec_b64 s[6:7], vcc
	s_cbranch_execz .LBB0_1325
	s_mul_i32 s34, s11, 0x810
	v_add_u32_e32 v20, s34, v79
	v_ashrrev_i32_e32 v21, 31, v20
	v_lshlrev_b64 v[20:21], 11, v[20:21]
	v_lshl_add_u64 v[20:21], s[4:5], 0, v[20:21]
	s_lshl_b32 s34, s92, 1
	s_mov_b32 s35, s93
	v_lshl_add_u64 v[20:21], v[20:21], 0, s[34:35]
	v_mov_b32_e32 v63, v12
	v_lshl_add_u64 v[20:21], v[20:21], 0, v[62:63]
	global_load_dwordx4 v[20:23], v[20:21], off
